# P3: half-0 x loads trickled into the K-loop (1 per K-step, counted vmcnt(1)), half-1 loads batched
# speedup vs baseline: 1.0063x; 1.0052x over previous
; #define STAGEB(KOFF, BUF) do { \
;     _Pragma("unroll") for (int i = 0; i < 4; ++i) { \
;       __builtin_amdgcn_global_load_lds((const unsigned*)(ga + i * rs + (KOFF)), (lds_u32*)(lbase + (BUF) * BIG_STAGE + i * 8192), 16, 0, 0); \
;       __builtin_amdgcn_global_load_lds((const unsigned*)(gb + i * rs + (KOFF)), (lds_u32*)(lbase + (BUF) * BIG_STAGE + 32768 + i * 8192), 16, 0, 0); } } while (0)
; DI void gemm_tile_big(const u16* __restrict__ A, const u16* __restrict__ Bt, const int K, const int m0, const int n0, char* smem, f32x4 (&acc)[8][4]) {
;   const int tid = threadIdx.x, lane = tid & 63, w = __builtin_amdgcn_readfirstlane(tid >> 6);
;   const int wm = w & 1, wn = w >> 1;
;   const int g = lane >> 4, r16 = lane & 15;
; #pragma unroll
;   for (int i = 0; i < 8; ++i)
; #pragma unroll
;     for (int j = 0; j < 4; ++j) acc[i][j] = f32x4{0.f, 0.f, 0.f, 0.f};
;   const int srow = tid >> 3, sc = tid & 7;
;   const int c = sc ^ ((srow >> 1) & 7);
;   const u16* ga = A + (size_t)(m0 + srow) * K + c * 8;
;   const u16* gb = Bt + (size_t)(n0 + srow) * K + c * 8;
;   const size_t rs = (size_t)64 * K;
;   __attribute__((address_space(3))) char* lbase = (__attribute__((address_space(3))) char*)(smem + tid * 16);
;     ...
;   const int KT = K / 64;
;   STAGEB(0, 0);
;   asm volatile("s_waitcnt vmcnt(0)" ::: "memory");
;   __builtin_amdgcn_s_barrier();
; DI void outproj_epilogue(const Params& p, const char* smem, const int m0, const int n0) {
;     ...
;     const int c = threadIdx.x + NT * i, row = c >> 5, ch = c & 31;
;     const float4 y = *(const float4*)(ct + row * CT_PITCH + 4 * ch);
;     const size_t o = (size_t)(m0 + row) * 1024 + n0 + 4 * ch;
.LBB0_290:
	s_ashr_i32 s10, s1, 31
	s_lshr_b32 s10, s10, 30
	s_add_i32 s10, s1, s10
	s_lshl_b32 s0, s0, 8
	s_and_b32 s10, s10, 0xfffffc
	v_or_b32_e32 v2, s0, v144
	s_sub_i32 s1, s1, s10
	v_ashrrev_i32_e32 v3, 31, v2
	s_lshl_b32 s26, s1, 8
	v_lshlrev_b64 v[2:3], 11, v[2:3]
	v_lshl_add_u64 v[138:139], v[132:133], 0, v[2:3]
	v_or_b32_e32 v2, s26, v144
	v_ashrrev_i32_e32 v3, 31, v2
	v_readfirstlane_b32 s10, v145
	v_lshlrev_b64 v[2:3], 11, v[2:3]
	s_mov_b32 m0, s10
	v_readfirstlane_b32 s10, v155
	v_lshl_add_u64 v[140:141], v[134:135], 0, v[2:3]
	global_load_lds_dwordx4 v[138:139], off
	s_mov_b32 m0, s10
	v_readfirstlane_b32 s10, v156
	global_load_lds_dwordx4 v[140:141], off
	v_lshl_add_u64 v[2:3], v[138:139], 0, s[18:19]
	s_mov_b32 m0, s10
	v_readfirstlane_b32 s10, v157
	global_load_lds_dwordx4 v[2:3], off
	v_lshl_add_u64 v[2:3], v[140:141], 0, s[18:19]
	s_mov_b32 m0, s10
	v_readfirstlane_b32 s10, v158
	global_load_lds_dwordx4 v[2:3], off
	v_lshl_add_u64 v[2:3], v[138:139], 0, s[20:21]
	s_mov_b32 m0, s10
	v_readfirstlane_b32 s10, v159
	global_load_lds_dwordx4 v[2:3], off
	v_lshl_add_u64 v[2:3], v[140:141], 0, s[20:21]
	s_mov_b32 m0, s10
	v_readfirstlane_b32 s10, v160
	global_load_lds_dwordx4 v[2:3], off
	v_lshl_add_u64 v[2:3], v[138:139], 0, s[22:23]
	s_mov_b32 m0, s10
	v_readfirstlane_b32 s10, v161
	global_load_lds_dwordx4 v[2:3], off
	v_lshl_add_u64 v[2:3], v[140:141], 0, s[22:23]
	s_mov_b32 m0, s10
	v_readfirstlane_b32 s1, v0
	global_load_lds_dwordx4 v[2:3], off
	s_lshr_b32 s10, s1, 1
	s_lshl_b32 s1, s1, 1
	s_waitcnt vmcnt(0)
	s_and_b32 s1, s1, 0x80
	s_and_b32 s10, s10, 0x1ffffc0
	v_or_b32_e32 v2, s1, v1
	v_mov_b32_e32 v70, 0
	v_add_lshl_u32 v162, v142, s10, 7
	v_lshlrev_b32_e32 v163, 7, v2
	s_mov_b32 s27, 0
	s_mov_b32 s1, 64
	v_mov_b32_e32 v71, v70
	v_mov_b32_e32 v72, v70
	v_mov_b32_e32 v73, v70
	v_mov_b32_e32 v2, v70
	v_mov_b32_e32 v3, v70
	v_mov_b32_e32 v4, v70
	v_mov_b32_e32 v5, v70
	v_mov_b32_e32 v6, v70
	v_mov_b32_e32 v7, v70
	v_mov_b32_e32 v8, v70
	v_mov_b32_e32 v9, v70
	v_mov_b32_e32 v10, v70
	v_mov_b32_e32 v11, v70
	v_mov_b32_e32 v12, v70
	v_mov_b32_e32 v13, v70
	v_mov_b32_e32 v14, v70
	v_mov_b32_e32 v15, v70
	v_mov_b32_e32 v16, v70
	v_mov_b32_e32 v17, v70
	v_mov_b32_e32 v18, v70
	v_mov_b32_e32 v19, v70
	v_mov_b32_e32 v20, v70
	v_mov_b32_e32 v21, v70
	v_mov_b32_e32 v22, v70
	v_mov_b32_e32 v23, v70
	v_mov_b32_e32 v24, v70
	v_mov_b32_e32 v25, v70
	v_mov_b32_e32 v26, v70
	v_mov_b32_e32 v27, v70
	v_mov_b32_e32 v28, v70
	v_mov_b32_e32 v29, v70
	v_mov_b32_e32 v30, v70
	v_mov_b32_e32 v31, v70
	v_mov_b32_e32 v32, v70
	v_mov_b32_e32 v33, v70
	v_mov_b32_e32 v34, v70
	v_mov_b32_e32 v35, v70
	v_mov_b32_e32 v36, v70
	v_mov_b32_e32 v37, v70
	v_mov_b32_e32 v38, v70
	v_mov_b32_e32 v39, v70
	v_mov_b32_e32 v40, v70
	v_mov_b32_e32 v41, v70
	v_mov_b32_e32 v42, v70
	v_mov_b32_e32 v43, v70
	v_mov_b32_e32 v44, v70
	v_mov_b32_e32 v45, v70
	v_mov_b32_e32 v46, v70
	v_mov_b32_e32 v47, v70
	v_mov_b32_e32 v48, v70
	v_mov_b32_e32 v49, v70
	v_mov_b32_e32 v50, v70
	v_mov_b32_e32 v51, v70
	v_mov_b32_e32 v52, v70
	v_mov_b32_e32 v53, v70
	v_mov_b32_e32 v54, v70
	v_mov_b32_e32 v55, v70
	v_mov_b32_e32 v56, v70
	v_mov_b32_e32 v57, v70
	v_mov_b32_e32 v58, v70
	v_mov_b32_e32 v59, v70
	v_mov_b32_e32 v60, v70
	v_mov_b32_e32 v61, v70
	v_mov_b32_e32 v62, v70
	v_mov_b32_e32 v63, v70
	v_mov_b32_e32 v64, v70
	v_mov_b32_e32 v65, v70
	v_mov_b32_e32 v66, v70
	v_mov_b32_e32 v67, v70
	v_mov_b32_e32 v68, v70
	v_mov_b32_e32 v69, v70
	v_mov_b32_e32 v74, v70
	v_mov_b32_e32 v75, v70
	v_mov_b32_e32 v76, v70
	v_mov_b32_e32 v77, v70
	v_mov_b32_e32 v78, v70
	v_mov_b32_e32 v79, v70
	v_mov_b32_e32 v80, v70
	v_mov_b32_e32 v81, v70
	v_mov_b32_e32 v82, v70
	v_mov_b32_e32 v83, v70
	v_mov_b32_e32 v84, v70
	v_mov_b32_e32 v85, v70
	v_mov_b32_e32 v86, v70
	v_mov_b32_e32 v87, v70
	v_mov_b32_e32 v88, v70
	v_mov_b32_e32 v89, v70
	v_mov_b32_e32 v90, v70
	v_mov_b32_e32 v91, v70
	v_mov_b32_e32 v92, v70
	v_mov_b32_e32 v93, v70
	v_mov_b32_e32 v94, v70
	v_mov_b32_e32 v95, v70
	v_mov_b32_e32 v96, v70
	v_mov_b32_e32 v97, v70
	v_mov_b32_e32 v98, v70
	v_mov_b32_e32 v99, v70
	v_mov_b32_e32 v100, v70
	v_mov_b32_e32 v101, v70
	v_mov_b32_e32 v102, v70
	v_mov_b32_e32 v103, v70
	v_mov_b32_e32 v104, v70
	v_mov_b32_e32 v105, v70
	v_mov_b32_e32 v106, v70
	v_mov_b32_e32 v107, v70
	v_mov_b32_e32 v108, v70
	v_mov_b32_e32 v109, v70
	v_mov_b32_e32 v110, v70
	v_mov_b32_e32 v111, v70
	v_mov_b32_e32 v112, v70
	v_mov_b32_e32 v113, v70
	v_mov_b32_e32 v114, v70
	v_mov_b32_e32 v115, v70
	v_mov_b32_e32 v116, v70
	v_mov_b32_e32 v117, v70
	v_mov_b32_e32 v118, v70
	v_mov_b32_e32 v119, v70
	v_mov_b32_e32 v120, v70
	v_mov_b32_e32 v121, v70
	v_mov_b32_e32 v122, v70
	v_mov_b32_e32 v123, v70
	v_mov_b32_e32 v124, v70
	v_mov_b32_e32 v125, v70
	v_mov_b32_e32 v126, v70
	v_mov_b32_e32 v127, v70
	v_mov_b32_e32 v128, v70
	v_mov_b32_e32 v129, v70
	v_add_u32_e32 v192, s0, v153
	v_add_u32_e32 v193, s0, v151
	v_add_u32_e32 v195, s0, v149
	v_or_b32_e32 v194, s26, v130
	v_lshl_add_u32 v192, v192, 10, v194
	v_lshl_add_u32 v193, v193, 10, v194
	v_lshl_add_u32 v195, v195, 10, v194
	v_add_u32_e32 v194, 0x8000, v192
	v_lshlrev_b32_e32 v192, 2, v192
	v_lshlrev_b32_e32 v193, 2, v193
	v_lshlrev_b32_e32 v194, 2, v194
	v_lshlrev_b32_e32 v195, 2, v195
	s_barrier
; #define MFMA16(a, b, c) __builtin_amdgcn_mfma_f32_16x16x32_bf16((a), (b), (c), 0, 0, 0)
; #define STAGEB(KOFF, BUF) do { \
;     _Pragma("unroll") for (int i = 0; i < 4; ++i) { \
;       __builtin_amdgcn_global_load_lds((const unsigned*)(ga + i * rs + (KOFF)), (lds_u32*)(lbase + (BUF) * BIG_STAGE + i * 8192), 16, 0, 0); \
;       __builtin_amdgcn_global_load_lds((const unsigned*)(gb + i * rs + (KOFF)), (lds_u32*)(lbase + (BUF) * BIG_STAGE + 32768 + i * 8192), 16, 0, 0); } } while (0)
; DI void gemm_tile_big(const u16* __restrict__ A, const u16* __restrict__ Bt, const int K, const int m0, const int n0, char* smem, f32x4 (&acc)[8][4]) {
;     ...
;   for (int kt = 0; kt < KT; ++kt) {
;     STAGEB((kt + 1 < KT ? kt + 1 : kt) * 64, (kt + 1) & 1);
;     const char* cur = smem + (kt & 1) * BIG_STAGE;
; #pragma unroll
;     for (int kk = 0; kk < 2; ++kk) {
;       const int cc = 4 * kk + g;
;       bf16x8 bfr[4];
; #pragma unroll
;       for (int ni = 0; ni < 4; ++ni) { const int row = 256 + 64 * wn + 16 * ni + r16; bfr[ni] = *(const bf16x8*)(cur + row * 128 + ((cc ^ ((row >> 1) & 7)) << 4)); }
; #pragma unroll
;       for (int mi = 0; mi < 8; ++mi) {
;         const int row = 128 * wm + 16 * mi + r16;
;         const bf16x8 af = *(const bf16x8*)(cur + row * 128 + ((cc ^ ((row >> 1) & 7)) << 4));
; #pragma unroll
;         for (int ni = 0; ni < 4; ++ni) acc[mi][ni] = MFMA16(af, bfr[ni], acc[mi][ni]);
; DI void outproj_epilogue(const Params& p, const char* smem, const int m0, const int n0) {
;     ...
;     const float4 xv = *(const float4*)(p.x + o), bv = *(const float4*)(p.b_out + n0 + 4 * ch);
.LBB0_291:
	s_cmp_lg_u32 s27, 0xf0000
	s_cselect_b32 s10, s1, 0x3c0
	s_add_i32 s28, s27, 0x10000
	s_lshl_b64 s[36:37], s[10:11], 1
	s_and_b32 s10, s28, 0x10000
	v_add_u32_e32 v180, s10, v145
	v_add_u32_e32 v182, 0x8000, v180
	v_readfirstlane_b32 s10, v180
	v_lshl_add_u64 v[164:165], v[138:139], 0, s[36:37]
	v_add_u32_e32 v183, 0x2000, v180
	v_readfirstlane_b32 s29, v182
	s_mov_b32 m0, s10
	v_lshl_add_u64 v[166:167], v[140:141], 0, s[36:37]
	v_add_u32_e32 v184, 0xa000, v180
	v_readfirstlane_b32 s35, v183
	global_load_lds_dwordx4 v[164:165], off
	s_mov_b32 m0, s29
	v_lshl_add_u64 v[168:169], v[164:165], 0, s[18:19]
	v_add_u32_e32 v185, 0x4000, v180
	v_readfirstlane_b32 s36, v184
	global_load_lds_dwordx4 v[166:167], off
	s_mov_b32 m0, s35
	v_lshl_add_u64 v[170:171], v[166:167], 0, s[18:19]
	v_add_u32_e32 v186, 0xc000, v180
	v_readfirstlane_b32 s37, v185
	global_load_lds_dwordx4 v[168:169], off
	s_mov_b32 m0, s36
	v_lshl_add_u64 v[172:173], v[164:165], 0, s[20:21]
	v_add_u32_e32 v187, 0x6000, v180
	v_readfirstlane_b32 s38, v186
	global_load_lds_dwordx4 v[170:171], off
	s_mov_b32 m0, s37
	v_lshl_add_u64 v[174:175], v[166:167], 0, s[20:21]
	v_add_u32_e32 v180, 0xe000, v180
	v_readfirstlane_b32 s39, v187
	global_load_lds_dwordx4 v[172:173], off
	s_mov_b32 m0, s38
	v_lshl_add_u64 v[176:177], v[164:165], 0, s[22:23]
	v_readfirstlane_b32 s40, v180
	global_load_lds_dwordx4 v[174:175], off
	s_mov_b32 m0, s39
	v_lshl_add_u64 v[178:179], v[166:167], 0, s[22:23]
	global_load_lds_dwordx4 v[176:177], off
	s_mov_b32 m0, s40
	s_and_b32 s27, s27, 0x10000
	global_load_lds_dwordx4 v[178:179], off
	s_lshr_b32 s98, s28, 16
	s_cmp_eq_u32 s98, 2
	s_cbranch_scc1 .Lmy_px_0
	s_cmp_eq_u32 s98, 3
	s_cbranch_scc1 .Lmy_px_1
	s_cmp_eq_u32 s98, 4
	s_cbranch_scc1 .Lmy_px_2
	s_cmp_eq_u32 s98, 5
	s_cbranch_scc1 .Lmy_px_3
	s_cmp_eq_u32 s98, 6
	s_cbranch_scc1 .Lmy_px_4
	s_cmp_eq_u32 s98, 7
	s_cbranch_scc1 .Lmy_px_5
	s_cmp_eq_u32 s98, 8
	s_cbranch_scc1 .Lmy_px_6
	s_cmp_eq_u32 s98, 9
	s_cbranch_scc1 .Lmy_px_7
	s_cmp_eq_u32 s98, 10
	s_cbranch_scc1 .Lmy_px_8
	s_cmp_eq_u32 s98, 11
	s_cbranch_scc1 .Lmy_px_9
	s_cmp_eq_u32 s98, 12
	s_cbranch_scc1 .Lmy_px_10
	s_cmp_eq_u32 s98, 13
	s_cbranch_scc1 .Lmy_px_11
	s_cmp_eq_u32 s98, 14
	s_cbranch_scc1 .Lmy_px_12
	global_load_dword v252, v192, s[52:53]
	s_branch .Lmy_px_done
.Lmy_px_0:
	global_load_dwordx4 v[196:199], v192, s[52:53]
	s_branch .Lmy_px_done
.Lmy_px_1:
	global_load_dwordx4 v[202:205], v193, s[52:53]
	s_branch .Lmy_px_done
.Lmy_px_2:
	global_load_dwordx4 v[206:209], v194, s[52:53]
	s_branch .Lmy_px_done
.Lmy_px_3:
	global_load_dwordx4 v[210:213], v195, s[52:53]
	s_branch .Lmy_px_done
.Lmy_px_4:
	s_add_u32 s100, s52, 0x40000
	s_addc_u32 s101, s53, 0
	global_load_dwordx4 v[214:217], v192, s[100:101]
	s_branch .Lmy_px_done
.Lmy_px_5:
	s_add_u32 s100, s52, 0x40000
	s_addc_u32 s101, s53, 0
	global_load_dwordx4 v[218:221], v193, s[100:101]
	s_branch .Lmy_px_done
.Lmy_px_6:
	s_add_u32 s100, s52, 0x40000
	s_addc_u32 s101, s53, 0
	global_load_dwordx4 v[222:225], v194, s[100:101]
	s_branch .Lmy_px_done
.Lmy_px_7:
	s_add_u32 s100, s52, 0x40000
	s_addc_u32 s101, s53, 0
	global_load_dwordx4 v[226:229], v195, s[100:101]
	s_branch .Lmy_px_done
.Lmy_px_8:
	s_add_u32 s100, s52, 0x80000
	s_addc_u32 s101, s53, 0
	global_load_dwordx4 v[230:233], v192, s[100:101]
	s_branch .Lmy_px_done
.Lmy_px_9:
	s_add_u32 s100, s52, 0x80000
	s_addc_u32 s101, s53, 0
	global_load_dwordx4 v[234:237], v193, s[100:101]
	s_branch .Lmy_px_done
.Lmy_px_10:
	s_add_u32 s100, s52, 0x80000
	s_addc_u32 s101, s53, 0
	global_load_dwordx4 v[240:243], v194, s[100:101]
	s_branch .Lmy_px_done
.Lmy_px_11:
	s_add_u32 s100, s52, 0x80000
	s_addc_u32 s101, s53, 0
	global_load_dwordx4 v[244:247], v195, s[100:101]
	s_branch .Lmy_px_done
.Lmy_px_12:
	s_add_u32 s100, s52, 0xc0000
	s_addc_u32 s101, s53, 0
	global_load_dwordx4 v[248:251], v192, s[100:101]
.Lmy_px_done:
	s_add_i32 s27, s27, 0
	v_add_u32_e32 v181, s27, v146
	v_add_u32_e32 v188, v181, v162
	v_add_u32_e32 v189, v181, v163
	ds_read_b128 v[164:167], v189
	ds_read_b128 v[168:171], v188
	ds_read_b128 v[172:175], v188 offset:2048
	ds_read_b128 v[176:179], v189 offset:2048
	ds_read_b128 v[180:183], v188 offset:4096
	ds_read_b128 v[184:187], v188 offset:6144
	s_waitcnt lgkmcnt(0)
	v_mfma_f32_16x16x32_bf16 v[126:129], v[164:167], v[168:171], v[126:129]
	s_add_i32 s1, s1, 64
	s_cmp_lg_u32 s28, 0x100000
	v_mfma_f32_16x16x32_bf16 v[122:125], v[164:167], v[172:175], v[122:125]
	v_mfma_f32_16x16x32_bf16 v[118:121], v[164:167], v[180:183], v[118:121]
	v_mfma_f32_16x16x32_bf16 v[114:117], v[164:167], v[184:187], v[114:117]
	v_mfma_f32_16x16x32_bf16 v[110:113], v[176:179], v[168:171], v[110:113]
	v_mfma_f32_16x16x32_bf16 v[106:109], v[176:179], v[172:175], v[106:109]
	v_mfma_f32_16x16x32_bf16 v[102:105], v[176:179], v[180:183], v[102:105]
	v_mfma_f32_16x16x32_bf16 v[98:101], v[176:179], v[184:187], v[98:101]
	ds_read_b128 v[164:167], v189 offset:4096
	ds_read_b128 v[176:179], v189 offset:6144
	s_waitcnt lgkmcnt(0)
	v_mfma_f32_16x16x32_bf16 v[94:97], v[164:167], v[168:171], v[94:97]
	v_mfma_f32_16x16x32_bf16 v[90:93], v[164:167], v[172:175], v[90:93]
	v_mfma_f32_16x16x32_bf16 v[86:89], v[164:167], v[180:183], v[86:89]
	v_mfma_f32_16x16x32_bf16 v[82:85], v[164:167], v[184:187], v[82:85]
	v_mfma_f32_16x16x32_bf16 v[78:81], v[176:179], v[168:171], v[78:81]
	v_mfma_f32_16x16x32_bf16 v[74:77], v[176:179], v[172:175], v[74:77]
	v_mfma_f32_16x16x32_bf16 v[66:69], v[176:179], v[180:183], v[66:69]
	v_mfma_f32_16x16x32_bf16 v[62:65], v[176:179], v[184:187], v[62:65]
	ds_read_b128 v[164:167], v189 offset:8192
	ds_read_b128 v[176:179], v189 offset:10240
	s_waitcnt lgkmcnt(0)
; #define MFMA16(a, b, c) __builtin_amdgcn_mfma_f32_16x16x32_bf16((a), (b), (c), 0, 0, 0)
; DI void gemm_tile_big(const u16* __restrict__ A, const u16* __restrict__ Bt, const int K, const int m0, const int n0, char* smem, f32x4 (&acc)[8][4]) {
;     ...
;     for (int kk = 0; kk < 2; ++kk) {
;       const int cc = 4 * kk + g;
;       bf16x8 bfr[4];
; #pragma unroll
;       for (int ni = 0; ni < 4; ++ni) { const int row = 256 + 64 * wn + 16 * ni + r16; bfr[ni] = *(const bf16x8*)(cur + row * 128 + ((cc ^ ((row >> 1) & 7)) << 4)); }
; #pragma unroll
;       for (int mi = 0; mi < 8; ++mi) {
;         const int row = 128 * wm + 16 * mi + r16;
;         const bf16x8 af = *(const bf16x8*)(cur + row * 128 + ((cc ^ ((row >> 1) & 7)) << 4));
; #pragma unroll
;         for (int ni = 0; ni < 4; ++ni) acc[mi][ni] = MFMA16(af, bfr[ni], acc[mi][ni]);
;       }
;     }
;     asm volatile("s_waitcnt vmcnt(0)" ::: "memory");
;     __builtin_amdgcn_s_barrier();
;   }
; template <int HF>
; DI void stage_acc_big(const f32x4 (&acc)[8][4], char* smem, const int g, const int r16) {
;   const int w = __builtin_amdgcn_readfirstlane(threadIdx.x >> 6), wm = w & 1, wn = w >> 1;
;   if ((wn >> 1) != HF) return;
	v_mfma_f32_16x16x32_bf16 v[58:61], v[164:167], v[168:171], v[58:61]
	v_mfma_f32_16x16x32_bf16 v[54:57], v[164:167], v[172:175], v[54:57]
	v_mfma_f32_16x16x32_bf16 v[50:53], v[164:167], v[180:183], v[50:53]
	v_mfma_f32_16x16x32_bf16 v[46:49], v[164:167], v[184:187], v[46:49]
	v_mfma_f32_16x16x32_bf16 v[42:45], v[176:179], v[168:171], v[42:45]
	v_mfma_f32_16x16x32_bf16 v[38:41], v[176:179], v[172:175], v[38:41]
	v_mfma_f32_16x16x32_bf16 v[34:37], v[176:179], v[180:183], v[34:37]
	v_mfma_f32_16x16x32_bf16 v[30:33], v[176:179], v[184:187], v[30:33]
	ds_read_b128 v[164:167], v189 offset:12288
	ds_read_b128 v[176:179], v189 offset:14336
	s_waitcnt lgkmcnt(0)
	v_mfma_f32_16x16x32_bf16 v[26:29], v[164:167], v[168:171], v[26:29]
	v_mfma_f32_16x16x32_bf16 v[22:25], v[164:167], v[172:175], v[22:25]
	v_mfma_f32_16x16x32_bf16 v[18:21], v[164:167], v[180:183], v[18:21]
	v_mfma_f32_16x16x32_bf16 v[14:17], v[164:167], v[184:187], v[14:17]
	v_add_u32_e32 v164, s27, v147
	v_add_u32_e32 v189, v164, v163
	v_add_u32_e32 v188, v164, v162
	ds_read_b128 v[164:167], v189
	v_mfma_f32_16x16x32_bf16 v[10:13], v[176:179], v[168:171], v[10:13]
	s_mov_b32 s27, s28
	v_mfma_f32_16x16x32_bf16 v[6:9], v[176:179], v[172:175], v[6:9]
	v_mfma_f32_16x16x32_bf16 v[2:5], v[176:179], v[180:183], v[2:5]
	v_mfma_f32_16x16x32_bf16 v[70:73], v[176:179], v[184:187], v[70:73]
	ds_read_b128 v[168:171], v188
	ds_read_b128 v[172:175], v188 offset:2048
	ds_read_b128 v[176:179], v189 offset:2048
	ds_read_b128 v[180:183], v188 offset:4096
	ds_read_b128 v[184:187], v188 offset:6144
	s_waitcnt lgkmcnt(0)
	v_mfma_f32_16x16x32_bf16 v[126:129], v[164:167], v[168:171], v[126:129]
	v_mfma_f32_16x16x32_bf16 v[122:125], v[164:167], v[172:175], v[122:125]
	v_mfma_f32_16x16x32_bf16 v[118:121], v[164:167], v[180:183], v[118:121]
	v_mfma_f32_16x16x32_bf16 v[114:117], v[164:167], v[184:187], v[114:117]
	v_mfma_f32_16x16x32_bf16 v[110:113], v[176:179], v[168:171], v[110:113]
	v_mfma_f32_16x16x32_bf16 v[106:109], v[176:179], v[172:175], v[106:109]
	v_mfma_f32_16x16x32_bf16 v[102:105], v[176:179], v[180:183], v[102:105]
	v_mfma_f32_16x16x32_bf16 v[98:101], v[176:179], v[184:187], v[98:101]
	ds_read_b128 v[164:167], v189 offset:4096
	ds_read_b128 v[176:179], v189 offset:6144
	s_waitcnt lgkmcnt(0)
	v_mfma_f32_16x16x32_bf16 v[94:97], v[164:167], v[168:171], v[94:97]
	v_mfma_f32_16x16x32_bf16 v[90:93], v[164:167], v[172:175], v[90:93]
	v_mfma_f32_16x16x32_bf16 v[86:89], v[164:167], v[180:183], v[86:89]
	v_mfma_f32_16x16x32_bf16 v[82:85], v[164:167], v[184:187], v[82:85]
	v_mfma_f32_16x16x32_bf16 v[78:81], v[176:179], v[168:171], v[78:81]
	v_mfma_f32_16x16x32_bf16 v[74:77], v[176:179], v[172:175], v[74:77]
	v_mfma_f32_16x16x32_bf16 v[66:69], v[176:179], v[180:183], v[66:69]
	v_mfma_f32_16x16x32_bf16 v[62:65], v[176:179], v[184:187], v[62:65]
	ds_read_b128 v[164:167], v189 offset:8192
	ds_read_b128 v[176:179], v189 offset:10240
	s_waitcnt lgkmcnt(0)
	v_mfma_f32_16x16x32_bf16 v[58:61], v[164:167], v[168:171], v[58:61]
	v_mfma_f32_16x16x32_bf16 v[54:57], v[164:167], v[172:175], v[54:57]
	v_mfma_f32_16x16x32_bf16 v[50:53], v[164:167], v[180:183], v[50:53]
	v_mfma_f32_16x16x32_bf16 v[46:49], v[164:167], v[184:187], v[46:49]
	v_mfma_f32_16x16x32_bf16 v[42:45], v[176:179], v[168:171], v[42:45]
	v_mfma_f32_16x16x32_bf16 v[38:41], v[176:179], v[172:175], v[38:41]
	v_mfma_f32_16x16x32_bf16 v[34:37], v[176:179], v[180:183], v[34:37]
	v_mfma_f32_16x16x32_bf16 v[30:33], v[176:179], v[184:187], v[30:33]
	ds_read_b128 v[164:167], v189 offset:12288
	ds_read_b128 v[176:179], v189 offset:14336
	s_waitcnt vmcnt(1)
	s_barrier
	s_waitcnt lgkmcnt(0)
	v_mfma_f32_16x16x32_bf16 v[26:29], v[164:167], v[168:171], v[26:29]
	v_mfma_f32_16x16x32_bf16 v[22:25], v[164:167], v[172:175], v[22:25]
	v_mfma_f32_16x16x32_bf16 v[18:21], v[164:167], v[180:183], v[18:21]
	v_mfma_f32_16x16x32_bf16 v[14:17], v[164:167], v[184:187], v[14:17]
	v_mfma_f32_16x16x32_bf16 v[10:13], v[176:179], v[168:171], v[10:13]
	v_mfma_f32_16x16x32_bf16 v[6:9], v[176:179], v[172:175], v[6:9]
	v_mfma_f32_16x16x32_bf16 v[2:5], v[176:179], v[180:183], v[2:5]
	v_mfma_f32_16x16x32_bf16 v[70:73], v[176:179], v[184:187], v[70:73]
	s_cbranch_scc1 .LBB0_291
	v_readfirstlane_b32 s1, v0
	s_cmpk_gt_u32 s1, 0xff
	s_cbranch_scc1 .LBB0_294
; template <int HF>
; DI void stage_acc_big(const f32x4 (&acc)[8][4], char* smem, const int g, const int r16) {
;   const int w = __builtin_amdgcn_readfirstlane(threadIdx.x >> 6), wm = w & 1, wn = w >> 1;
;   if ((wn >> 1) != HF) return;
;   float* ct = (float*)smem;
; #pragma unroll
;   for (int mi = 0; mi < 8; ++mi)
; #pragma unroll
;     for (int ni = 0; ni < 4; ++ni)
; #pragma unroll
;       for (int j = 0; j < 4; ++j) ct[(128 * wm + 16 * mi + 4 * g + j) * CT_PITCH + 64 * (wn & 1) + 16 * ni + r16] = acc[mi][ni][j];
; }
; DI void outproj_epilogue(const Params& p, const char* smem, const int m0, const int n0) {
;   u16* rbuf = (u16*)(p.ws + WS_PU);
;   const float* ct = (const float*)smem;
; #pragma unroll 4
;   for (int i = 0; i < 16; ++i) {
;     const int c = threadIdx.x + NT * i, row = c >> 5, ch = c & 31;
;     const float4 y = *(const float4*)(ct + row * CT_PITCH + 4 * ch);
;     const size_t o = (size_t)(m0 + row) * 1024 + n0 + 4 * ch;
;     const float4 xv = *(const float4*)(p.x + o), bv = *(const float4*)(p.b_out + n0 + 4 * ch);
	s_lshl_b32 s1, s1, 1
	s_and_b32 s10, s1, 0x80
	v_or_b32_e32 v138, s10, v148
	s_and_b32 s1, s1, 0x100
	v_mul_u32_u24_e32 v138, 0x210, v138
	v_add3_u32 v138, v143, s1, v138
	v_add_u32_e32 v139, 0x400, v138
	ds_write2_b32 v138, v126, v122 offset1:16
	ds_write2_b32 v138, v127, v123 offset0:132 offset1:148
	ds_write2_b32 v139, v128, v124 offset0:8 offset1:24
	ds_write2_b32 v139, v129, v125 offset0:140 offset1:156
	ds_write2_b32 v138, v118, v114 offset0:32 offset1:48
	ds_write2_b32 v138, v119, v115 offset0:164 offset1:180
	ds_write2_b32 v139, v120, v116 offset0:40 offset1:56
	ds_write2_b32 v139, v121, v117 offset0:172 offset1:188
	v_add_u32_e32 v139, 0x2000, v138
	v_add_u32_e32 v140, 0x2400, v138
	ds_write2_b32 v139, v110, v106 offset0:64 offset1:80
	ds_write2_b32 v139, v111, v107 offset0:196 offset1:212
	ds_write2_b32 v140, v112, v108 offset0:72 offset1:88
	ds_write2_b32 v140, v113, v109 offset0:204 offset1:220
	ds_write2_b32 v139, v102, v98 offset0:96 offset1:112
	ds_write2_b32 v139, v103, v99 offset0:228 offset1:244
	ds_write2_b32 v140, v104, v100 offset0:104 offset1:120
	ds_write2_b32 v140, v105, v101 offset0:236 offset1:252
	v_add_u32_e32 v139, 0x4000, v138
	v_add_u32_e32 v140, 0x4400, v138
	v_add_u32_e32 v141, 0x4800, v138
	ds_write2_b32 v139, v94, v90 offset0:128 offset1:144
	ds_write2_b32 v140, v95, v91 offset0:4 offset1:20
	ds_write2_b32 v140, v96, v92 offset0:136 offset1:152
	ds_write2_b32 v141, v97, v93 offset0:12 offset1:28
	ds_write2_b32 v139, v86, v82 offset0:160 offset1:176
	ds_write2_b32 v140, v87, v83 offset0:36 offset1:52
	ds_write2_b32 v140, v88, v84 offset0:168 offset1:184
	ds_write2_b32 v141, v89, v85 offset0:44 offset1:60
	v_add_u32_e32 v139, 0x6000, v138
	v_add_u32_e32 v140, 0x6400, v138
	v_add_u32_e32 v141, 0x6800, v138
	ds_write2_b32 v139, v78, v74 offset0:192 offset1:208
	ds_write2_b32 v140, v79, v75 offset0:68 offset1:84
	ds_write2_b32 v140, v80, v76 offset0:200 offset1:216
	ds_write2_b32 v141, v81, v77 offset0:76 offset1:92
	ds_write2_b32 v139, v66, v62 offset0:224 offset1:240
	ds_write2_b32 v140, v67, v63 offset0:100 offset1:116
	ds_write2_b32 v140, v68, v64 offset0:232 offset1:248
	ds_write2_b32 v141, v69, v65 offset0:108 offset1:124
	v_add_u32_e32 v139, 0x8400, v138
	v_add_u32_e32 v140, 0x8800, v138
	ds_write2_b32 v139, v58, v54 offset1:16
	ds_write2_b32 v139, v59, v55 offset0:132 offset1:148
	ds_write2_b32 v140, v60, v56 offset0:8 offset1:24
	ds_write2_b32 v140, v61, v57 offset0:140 offset1:156
	ds_write2_b32 v139, v50, v46 offset0:32 offset1:48
	ds_write2_b32 v139, v51, v47 offset0:164 offset1:180
	ds_write2_b32 v140, v52, v48 offset0:40 offset1:56
	ds_write2_b32 v140, v53, v49 offset0:172 offset1:188
	v_add_u32_e32 v139, 0xa400, v138
	v_add_u32_e32 v140, 0xa800, v138
	ds_write2_b32 v139, v42, v38 offset0:64 offset1:80
	ds_write2_b32 v139, v43, v39 offset0:196 offset1:212
	ds_write2_b32 v140, v44, v40 offset0:72 offset1:88
	ds_write2_b32 v140, v45, v41 offset0:204 offset1:220
	ds_write2_b32 v139, v34, v30 offset0:96 offset1:112
	ds_write2_b32 v139, v35, v31 offset0:228 offset1:244
	ds_write2_b32 v140, v36, v32 offset0:104 offset1:120
	ds_write2_b32 v140, v37, v33 offset0:236 offset1:252
	v_add_u32_e32 v139, 0xc400, v138
	v_add_u32_e32 v140, 0xc800, v138
	v_add_u32_e32 v141, 0xcc00, v138
	ds_write2_b32 v139, v26, v22 offset0:128 offset1:144
	ds_write2_b32 v140, v27, v23 offset0:4 offset1:20
	ds_write2_b32 v140, v28, v24 offset0:136 offset1:152
	ds_write2_b32 v141, v29, v25 offset0:12 offset1:28
	ds_write2_b32 v139, v18, v14 offset0:160 offset1:176
	ds_write2_b32 v140, v19, v15 offset0:36 offset1:52
	ds_write2_b32 v140, v20, v16 offset0:168 offset1:184
	ds_write2_b32 v141, v21, v17 offset0:44 offset1:60
	v_add_u32_e32 v139, 0xe400, v138
	v_add_u32_e32 v140, 0xe800, v138
	v_add_u32_e32 v138, 0xec00, v138
	ds_write2_b32 v139, v10, v6 offset0:192 offset1:208
	ds_write2_b32 v140, v11, v7 offset0:68 offset1:84
	ds_write2_b32 v140, v12, v8 offset0:200 offset1:216
	ds_write2_b32 v138, v13, v9 offset0:76 offset1:92
	ds_write2_b32 v139, v2, v70 offset0:224 offset1:240
	ds_write2_b32 v140, v3, v71 offset0:100 offset1:116
	ds_write2_b32 v140, v4, v72 offset0:232 offset1:248
	ds_write2_b32 v138, v5, v73 offset0:108 offset1:124
.LBB0_294:
	s_ashr_i32 s27, s26, 31
	v_mov_b32_e32 v141, s27
	v_or_b32_e32 v140, s26, v130
	v_lshl_add_u64 v[138:139], s[26:27], 2, v[136:137]
	v_add_u32_e32 v162, s0, v149
	v_add_u32_e32 v163, s0, v151
	v_add_u32_e32 v164, s0, v153
	s_mov_b32 s0, 0
	v_mov_b32_e32 v165, v154
	v_mov_b32_e32 v166, v152
	v_mov_b32_e32 v167, v150
	v_lshrrev_b32_e32 v176, 1, v192
	v_lshrrev_b32_e32 v177, 1, v193
	v_lshrrev_b32_e32 v178, 1, v194
	v_lshrrev_b32_e32 v179, 1, v195
	global_load_dwordx4 v[252:255], v[138:139], off
	s_add_u32 s100, s52, 0xc0000
	s_addc_u32 s101, s53, 0
	global_load_dwordx4 v[168:171], v193, s[100:101]
	global_load_dwordx4 v[172:175], v194, s[100:101]
	global_load_dwordx4 v[188:191], v195, s[100:101]
	s_waitcnt lgkmcnt(0)
	s_barrier
; DI unsigned pack2(float a, float b) { const f32x2 v = {a, b}; const bf16x2_t r = __builtin_convertvector(v, bf16x2_t); return __builtin_bit_cast(unsigned, r); }
; DI void outproj_epilogue(const Params& p, const char* smem, const int m0, const int n0) {
;     ...
; #pragma unroll 4
;   for (int i = 0; i < 16; ++i) {
;     const int c = threadIdx.x + NT * i, row = c >> 5, ch = c & 31;
;     const float4 y = *(const float4*)(ct + row * CT_PITCH + 4 * ch);
;     const size_t o = (size_t)(m0 + row) * 1024 + n0 + 4 * ch;
;     const float4 xv = *(const float4*)(p.x + o), bv = *(const float4*)(p.b_out + n0 + 4 * ch);
;     uint2 r; r.x = pack2(ALPHA * xv.x + y.x + bv.x, ALPHA * xv.y + y.y + bv.y); r.y = pack2(ALPHA * xv.z + y.z + bv.z, ALPHA * xv.w + y.w + bv.w);
;     *(uint2*)(rbuf + o) = r;
;   }
	s_mov_b64 s[98:99], s[14:15]
	ds_read_b128 v[180:183], v165
	ds_read_b128 v[184:187], v166
	s_waitcnt vmcnt(3) lgkmcnt(1)
	v_pk_fma_f32 v[196:197], v[196:197], s[24:25], v[180:181] op_sel_hi:[1,0,1]
	v_pk_fma_f32 v[198:199], v[198:199], s[24:25], v[182:183] op_sel_hi:[1,0,1]
	ds_read_b128 v[180:183], v165 offset:16896
	v_pk_add_f32 v[196:197], v[196:197], v[252:253]
	v_pk_add_f32 v[198:199], v[198:199], v[254:255]
	v_cvt_pk_bf16_f32 v196, v196, v197
	v_cvt_pk_bf16_f32 v197, v198, v199
	global_store_dwordx2 v176, v[196:197], s[98:99]
	s_waitcnt lgkmcnt(1)
	v_pk_fma_f32 v[202:203], v[202:203], s[24:25], v[184:185] op_sel_hi:[1,0,1]
	v_pk_fma_f32 v[204:205], v[204:205], s[24:25], v[186:187] op_sel_hi:[1,0,1]
	ds_read_b128 v[184:187], v167
	v_pk_add_f32 v[202:203], v[202:203], v[252:253]
	v_pk_add_f32 v[204:205], v[204:205], v[254:255]
	v_cvt_pk_bf16_f32 v202, v202, v203
	v_cvt_pk_bf16_f32 v203, v204, v205
	global_store_dwordx2 v177, v[202:203], s[98:99]
	s_waitcnt lgkmcnt(1)
	v_pk_fma_f32 v[206:207], v[206:207], s[24:25], v[180:181] op_sel_hi:[1,0,1]
	v_pk_fma_f32 v[208:209], v[208:209], s[24:25], v[182:183] op_sel_hi:[1,0,1]
	v_pk_add_f32 v[206:207], v[206:207], v[252:253]
	v_pk_add_f32 v[208:209], v[208:209], v[254:255]
	v_cvt_pk_bf16_f32 v206, v206, v207
	v_cvt_pk_bf16_f32 v207, v208, v209
	global_store_dwordx2 v178, v[206:207], s[98:99]
	s_waitcnt lgkmcnt(0)
	v_pk_fma_f32 v[210:211], v[210:211], s[24:25], v[184:185] op_sel_hi:[1,0,1]
	v_pk_fma_f32 v[212:213], v[212:213], s[24:25], v[186:187] op_sel_hi:[1,0,1]
	v_pk_add_f32 v[210:211], v[210:211], v[252:253]
	v_pk_add_f32 v[212:213], v[212:213], v[254:255]
	v_cvt_pk_bf16_f32 v210, v210, v211
	v_cvt_pk_bf16_f32 v211, v212, v213
	global_store_dwordx2 v179, v[210:211], s[98:99]
	v_add_u32_e32 v165, 0x8400, v165
	v_add_u32_e32 v166, 0x8400, v166
	v_add_u32_e32 v167, 0x8400, v167
	s_add_u32 s98, s98, 0x20000
	s_addc_u32 s99, s99, 0
	ds_read_b128 v[180:183], v165
	ds_read_b128 v[184:187], v166
	s_waitcnt lgkmcnt(1)
	v_pk_fma_f32 v[214:215], v[214:215], s[24:25], v[180:181] op_sel_hi:[1,0,1]
	v_pk_fma_f32 v[216:217], v[216:217], s[24:25], v[182:183] op_sel_hi:[1,0,1]
	ds_read_b128 v[180:183], v165 offset:16896
	v_pk_add_f32 v[214:215], v[214:215], v[252:253]
	v_pk_add_f32 v[216:217], v[216:217], v[254:255]
	v_cvt_pk_bf16_f32 v214, v214, v215
	v_cvt_pk_bf16_f32 v215, v216, v217
	global_store_dwordx2 v176, v[214:215], s[98:99]
	s_waitcnt lgkmcnt(1)
	v_pk_fma_f32 v[218:219], v[218:219], s[24:25], v[184:185] op_sel_hi:[1,0,1]
	v_pk_fma_f32 v[220:221], v[220:221], s[24:25], v[186:187] op_sel_hi:[1,0,1]
	ds_read_b128 v[184:187], v167
	v_pk_add_f32 v[218:219], v[218:219], v[252:253]
	v_pk_add_f32 v[220:221], v[220:221], v[254:255]
	v_cvt_pk_bf16_f32 v218, v218, v219
	v_cvt_pk_bf16_f32 v219, v220, v221
	global_store_dwordx2 v177, v[218:219], s[98:99]
	s_waitcnt lgkmcnt(1)
	v_pk_fma_f32 v[222:223], v[222:223], s[24:25], v[180:181] op_sel_hi:[1,0,1]
	v_pk_fma_f32 v[224:225], v[224:225], s[24:25], v[182:183] op_sel_hi:[1,0,1]
	v_pk_add_f32 v[222:223], v[222:223], v[252:253]
	v_pk_add_f32 v[224:225], v[224:225], v[254:255]
	v_cvt_pk_bf16_f32 v222, v222, v223
	v_cvt_pk_bf16_f32 v223, v224, v225
	global_store_dwordx2 v178, v[222:223], s[98:99]
	s_waitcnt lgkmcnt(0)
	v_pk_fma_f32 v[226:227], v[226:227], s[24:25], v[184:185] op_sel_hi:[1,0,1]
	v_pk_fma_f32 v[228:229], v[228:229], s[24:25], v[186:187] op_sel_hi:[1,0,1]
	v_pk_add_f32 v[226:227], v[226:227], v[252:253]
	v_pk_add_f32 v[228:229], v[228:229], v[254:255]
	v_cvt_pk_bf16_f32 v226, v226, v227
	v_cvt_pk_bf16_f32 v227, v228, v229
	global_store_dwordx2 v179, v[226:227], s[98:99]
	v_add_u32_e32 v165, 0x8400, v165
	v_add_u32_e32 v166, 0x8400, v166
	v_add_u32_e32 v167, 0x8400, v167
	s_add_u32 s98, s98, 0x20000
	s_addc_u32 s99, s99, 0
	ds_read_b128 v[180:183], v165
	ds_read_b128 v[184:187], v166
	s_waitcnt lgkmcnt(1)
	v_pk_fma_f32 v[230:231], v[230:231], s[24:25], v[180:181] op_sel_hi:[1,0,1]
	v_pk_fma_f32 v[232:233], v[232:233], s[24:25], v[182:183] op_sel_hi:[1,0,1]
	ds_read_b128 v[180:183], v165 offset:16896
	v_pk_add_f32 v[230:231], v[230:231], v[252:253]
	v_pk_add_f32 v[232:233], v[232:233], v[254:255]
	v_cvt_pk_bf16_f32 v230, v230, v231
	v_cvt_pk_bf16_f32 v231, v232, v233
	global_store_dwordx2 v176, v[230:231], s[98:99]
	s_waitcnt lgkmcnt(1)
	v_pk_fma_f32 v[234:235], v[234:235], s[24:25], v[184:185] op_sel_hi:[1,0,1]
	v_pk_fma_f32 v[236:237], v[236:237], s[24:25], v[186:187] op_sel_hi:[1,0,1]
	ds_read_b128 v[184:187], v167
	v_pk_add_f32 v[234:235], v[234:235], v[252:253]
	v_pk_add_f32 v[236:237], v[236:237], v[254:255]
	v_cvt_pk_bf16_f32 v234, v234, v235
	v_cvt_pk_bf16_f32 v235, v236, v237
	global_store_dwordx2 v177, v[234:235], s[98:99]
	s_waitcnt lgkmcnt(1)
	v_pk_fma_f32 v[240:241], v[240:241], s[24:25], v[180:181] op_sel_hi:[1,0,1]
	v_pk_fma_f32 v[242:243], v[242:243], s[24:25], v[182:183] op_sel_hi:[1,0,1]
	v_pk_add_f32 v[240:241], v[240:241], v[252:253]
	v_pk_add_f32 v[242:243], v[242:243], v[254:255]
	v_cvt_pk_bf16_f32 v240, v240, v241
	v_cvt_pk_bf16_f32 v241, v242, v243
	global_store_dwordx2 v178, v[240:241], s[98:99]
	s_waitcnt lgkmcnt(0)
	v_pk_fma_f32 v[244:245], v[244:245], s[24:25], v[184:185] op_sel_hi:[1,0,1]
	v_pk_fma_f32 v[246:247], v[246:247], s[24:25], v[186:187] op_sel_hi:[1,0,1]
	v_pk_add_f32 v[244:245], v[244:245], v[252:253]
	v_pk_add_f32 v[246:247], v[246:247], v[254:255]
	v_cvt_pk_bf16_f32 v244, v244, v245
	v_cvt_pk_bf16_f32 v245, v246, v247
	global_store_dwordx2 v179, v[244:245], s[98:99]
	v_add_u32_e32 v165, 0x8400, v165
	v_add_u32_e32 v166, 0x8400, v166
	v_add_u32_e32 v167, 0x8400, v167
	s_add_u32 s98, s98, 0x20000
	s_addc_u32 s99, s99, 0
	ds_read_b128 v[180:183], v165
	ds_read_b128 v[184:187], v166
	s_waitcnt lgkmcnt(1)
; DI unsigned pack2(float a, float b) { const f32x2 v = {a, b}; const bf16x2_t r = __builtin_convertvector(v, bf16x2_t); return __builtin_bit_cast(unsigned, r); }
; template <int HF>
; DI void stage_acc_big(const f32x4 (&acc)[8][4], char* smem, const int g, const int r16) {
;   const int w = __builtin_amdgcn_readfirstlane(threadIdx.x >> 6), wm = w & 1, wn = w >> 1;
;   if ((wn >> 1) != HF) return;
;   float* ct = (float*)smem;
; #pragma unroll
;   for (int mi = 0; mi < 8; ++mi)
; #pragma unroll
;     for (int ni = 0; ni < 4; ++ni)
; #pragma unroll
;       for (int j = 0; j < 4; ++j) ct[(128 * wm + 16 * mi + 4 * g + j) * CT_PITCH + 64 * (wn & 1) + 16 * ni + r16] = acc[mi][ni][j];
; }
; DI void outproj_epilogue(const Params& p, const char* smem, const int m0, const int n0) {
;     ...
; #pragma unroll 4
;   for (int i = 0; i < 16; ++i) {
;     const int c = threadIdx.x + NT * i, row = c >> 5, ch = c & 31;
;     const float4 y = *(const float4*)(ct + row * CT_PITCH + 4 * ch);
;     const size_t o = (size_t)(m0 + row) * 1024 + n0 + 4 * ch;
;     const float4 xv = *(const float4*)(p.x + o), bv = *(const float4*)(p.b_out + n0 + 4 * ch);
;     uint2 r; r.x = pack2(ALPHA * xv.x + y.x + bv.x, ALPHA * xv.y + y.y + bv.y); r.y = pack2(ALPHA * xv.z + y.z + bv.z, ALPHA * xv.w + y.w + bv.w);
;     *(uint2*)(rbuf + o) = r;
;   }
	v_pk_fma_f32 v[248:249], v[248:249], s[24:25], v[180:181] op_sel_hi:[1,0,1]
	v_pk_fma_f32 v[250:251], v[250:251], s[24:25], v[182:183] op_sel_hi:[1,0,1]
	ds_read_b128 v[180:183], v165 offset:16896
	v_pk_add_f32 v[248:249], v[248:249], v[252:253]
	v_pk_add_f32 v[250:251], v[250:251], v[254:255]
	v_cvt_pk_bf16_f32 v248, v248, v249
	v_cvt_pk_bf16_f32 v249, v250, v251
	global_store_dwordx2 v176, v[248:249], s[98:99]
	s_waitcnt vmcnt(15) lgkmcnt(1)
	v_pk_fma_f32 v[168:169], v[168:169], s[24:25], v[184:185] op_sel_hi:[1,0,1]
	v_pk_fma_f32 v[170:171], v[170:171], s[24:25], v[186:187] op_sel_hi:[1,0,1]
	ds_read_b128 v[184:187], v167
	v_pk_add_f32 v[168:169], v[168:169], v[252:253]
	v_pk_add_f32 v[170:171], v[170:171], v[254:255]
	v_cvt_pk_bf16_f32 v168, v168, v169
	v_cvt_pk_bf16_f32 v169, v170, v171
	global_store_dwordx2 v177, v[168:169], s[98:99]
	s_waitcnt vmcnt(15) lgkmcnt(1)
	v_pk_fma_f32 v[172:173], v[172:173], s[24:25], v[180:181] op_sel_hi:[1,0,1]
	v_pk_fma_f32 v[174:175], v[174:175], s[24:25], v[182:183] op_sel_hi:[1,0,1]
	v_pk_add_f32 v[172:173], v[172:173], v[252:253]
	v_pk_add_f32 v[174:175], v[174:175], v[254:255]
	v_cvt_pk_bf16_f32 v172, v172, v173
	v_cvt_pk_bf16_f32 v173, v174, v175
	global_store_dwordx2 v178, v[172:173], s[98:99]
	s_waitcnt vmcnt(15) lgkmcnt(0)
	v_pk_fma_f32 v[188:189], v[188:189], s[24:25], v[184:185] op_sel_hi:[1,0,1]
	v_pk_fma_f32 v[190:191], v[190:191], s[24:25], v[186:187] op_sel_hi:[1,0,1]
	v_pk_add_f32 v[188:189], v[188:189], v[252:253]
	v_pk_add_f32 v[190:191], v[190:191], v[254:255]
	v_cvt_pk_bf16_f32 v188, v188, v189
	v_cvt_pk_bf16_f32 v189, v190, v191
	global_store_dwordx2 v179, v[188:189], s[98:99]
	v_readfirstlane_b32 s0, v0
	s_and_b32 s1, s0, 0xffffff00
	s_cmpk_lg_i32 s1, 0x100
	s_barrier
	s_cbranch_scc1 .LBB0_298
	s_lshl_b32 s0, s0, 1
	s_and_b32 s1, s0, 0x80
	v_or_b32_e32 v140, s1, v148
	s_and_b32 s0, s0, 0x100
	v_mul_u32_u24_e32 v140, 0x210, v140
	v_add3_u32 v140, v143, s0, v140
	ds_write2_b32 v140, v126, v122 offset1:16
	ds_write2_b32 v140, v127, v123 offset0:132 offset1:148
	v_add_u32_e32 v122, 0x400, v140
	ds_write2_b32 v122, v128, v124 offset0:8 offset1:24
	ds_write2_b32 v122, v129, v125 offset0:140 offset1:156
	ds_write2_b32 v140, v118, v114 offset0:32 offset1:48
	ds_write2_b32 v140, v119, v115 offset0:164 offset1:180
	ds_write2_b32 v122, v120, v116 offset0:40 offset1:56
	ds_write2_b32 v122, v121, v117 offset0:172 offset1:188
	v_add_u32_e32 v114, 0x2000, v140
	ds_write2_b32 v114, v110, v106 offset0:64 offset1:80
	ds_write2_b32 v114, v111, v107 offset0:196 offset1:212
	v_add_u32_e32 v106, 0x2400, v140
	ds_write2_b32 v106, v112, v108 offset0:72 offset1:88
	ds_write2_b32 v106, v113, v109 offset0:204 offset1:220
	ds_write2_b32 v114, v102, v98 offset0:96 offset1:112
	ds_write2_b32 v114, v103, v99 offset0:228 offset1:244
	ds_write2_b32 v106, v104, v100 offset0:104 offset1:120
	ds_write2_b32 v106, v105, v101 offset0:236 offset1:252
	v_add_u32_e32 v98, 0x4000, v140
	ds_write2_b32 v98, v94, v90 offset0:128 offset1:144
	v_add_u32_e32 v90, 0x4400, v140
	ds_write2_b32 v90, v95, v91 offset0:4 offset1:20
	ds_write2_b32 v90, v96, v92 offset0:136 offset1:152
	v_add_u32_e32 v91, 0x4800, v140
	ds_write2_b32 v91, v97, v93 offset0:12 offset1:28
	ds_write2_b32 v98, v86, v82 offset0:160 offset1:176
	ds_write2_b32 v90, v87, v83 offset0:36 offset1:52
	ds_write2_b32 v90, v88, v84 offset0:168 offset1:184
	ds_write2_b32 v91, v89, v85 offset0:44 offset1:60
	v_add_u32_e32 v82, 0x6000, v140
	ds_write2_b32 v82, v78, v74 offset0:192 offset1:208
	v_add_u32_e32 v74, 0x6400, v140
	ds_write2_b32 v74, v79, v75 offset0:68 offset1:84
	ds_write2_b32 v74, v80, v76 offset0:200 offset1:216
	v_add_u32_e32 v75, 0x6800, v140
	ds_write2_b32 v75, v81, v77 offset0:76 offset1:92
	ds_write2_b32 v82, v66, v62 offset0:224 offset1:240
	ds_write2_b32 v74, v67, v63 offset0:100 offset1:116
	ds_write2_b32 v74, v68, v64 offset0:232 offset1:248
	ds_write2_b32 v75, v69, v65 offset0:108 offset1:124
	v_add_u32_e32 v62, 0x8400, v140
	ds_write2_b32 v62, v58, v54 offset1:16
	ds_write2_b32 v62, v59, v55 offset0:132 offset1:148
	v_add_u32_e32 v54, 0x8800, v140
	ds_write2_b32 v54, v60, v56 offset0:8 offset1:24
	ds_write2_b32 v54, v61, v57 offset0:140 offset1:156
	ds_write2_b32 v62, v50, v46 offset0:32 offset1:48
	ds_write2_b32 v62, v51, v47 offset0:164 offset1:180
	ds_write2_b32 v54, v52, v48 offset0:40 offset1:56
	ds_write2_b32 v54, v53, v49 offset0:172 offset1:188
	v_add_u32_e32 v46, 0xa400, v140
	ds_write2_b32 v46, v42, v38 offset0:64 offset1:80
	ds_write2_b32 v46, v43, v39 offset0:196 offset1:212
	v_add_u32_e32 v38, 0xa800, v140
	ds_write2_b32 v38, v44, v40 offset0:72 offset1:88
	ds_write2_b32 v38, v45, v41 offset0:204 offset1:220
	ds_write2_b32 v46, v34, v30 offset0:96 offset1:112
	ds_write2_b32 v46, v35, v31 offset0:228 offset1:244
	ds_write2_b32 v38, v36, v32 offset0:104 offset1:120
	ds_write2_b32 v38, v37, v33 offset0:236 offset1:252
	v_add_u32_e32 v30, 0xc400, v140
	ds_write2_b32 v30, v26, v22 offset0:128 offset1:144
	v_add_u32_e32 v22, 0xc800, v140
	ds_write2_b32 v22, v27, v23 offset0:4 offset1:20
	ds_write2_b32 v22, v28, v24 offset0:136 offset1:152
	v_add_u32_e32 v23, 0xcc00, v140
	ds_write2_b32 v23, v29, v25 offset0:12 offset1:28
	ds_write2_b32 v30, v18, v14 offset0:160 offset1:176
	ds_write2_b32 v22, v19, v15 offset0:36 offset1:52
	ds_write2_b32 v22, v20, v16 offset0:168 offset1:184
	ds_write2_b32 v23, v21, v17 offset0:44 offset1:60
	v_add_u32_e32 v14, 0xe400, v140
	ds_write2_b32 v14, v10, v6 offset0:192 offset1:208
	v_add_u32_e32 v6, 0xe800, v140
	ds_write2_b32 v6, v11, v7 offset0:68 offset1:84
	ds_write2_b32 v6, v12, v8 offset0:200 offset1:216
	v_add_u32_e32 v7, 0xec00, v140
	ds_write2_b32 v7, v13, v9 offset0:76 offset1:92
	ds_write2_b32 v14, v2, v70 offset0:224 offset1:240
	ds_write2_b32 v6, v3, v71 offset0:100 offset1:116
	ds_write2_b32 v6, v4, v72 offset0:232 offset1:248
	ds_write2_b32 v7, v5, v73 offset0:108 offset1:124
; DI unsigned pack2(float a, float b) { const f32x2 v = {a, b}; const bf16x2_t r = __builtin_convertvector(v, bf16x2_t); return __builtin_bit_cast(unsigned, r); }
; DI void outproj_epilogue(const Params& p, const char* smem, const int m0, const int n0) {
;   u16* rbuf = (u16*)(p.ws + WS_PU);
;   const float* ct = (const float*)smem;
; #pragma unroll 4
;   for (int i = 0; i < 16; ++i) {
;     const int c = threadIdx.x + NT * i, row = c >> 5, ch = c & 31;
;     const float4 y = *(const float4*)(ct + row * CT_PITCH + 4 * ch);
;     const size_t o = (size_t)(m0 + row) * 1024 + n0 + 4 * ch;
;     const float4 xv = *(const float4*)(p.x + o), bv = *(const float4*)(p.b_out + n0 + 4 * ch);
;     uint2 r; r.x = pack2(ALPHA * xv.x + y.x + bv.x, ALPHA * xv.y + y.y + bv.y); r.y = pack2(ALPHA * xv.z + y.z + bv.z, ALPHA * xv.w + y.w + bv.w);
;     *(uint2*)(rbuf + o) = r;
;   }
; DI void phase_outproj(const Params& p, char* smem) {
;     ...
;     stage_acc_big<1>(acc, smem, g, r16);
;     __syncthreads();
;     outproj_epilogue(p, smem, m0, n0b + 128);
.LBB0_298:
	s_or_b32 s0, s26, 0x80
	s_ashr_i32 s1, s0, 31
	v_mov_b32_e32 v3, s1
	v_or_b32_e32 v2, s0, v130
	v_lshl_add_u64 v[4:5], s[26:27], 0, v[130:131]
	s_mov_b32 s0, 0
	v_mov_b32_e32 v6, v154
	v_mov_b32_e32 v7, v152
	v_mov_b32_e32 v8, v150
	v_lshl_add_u32 v180, v164, 10, v4
	v_lshl_add_u32 v181, v163, 10, v4
	v_lshl_add_u32 v183, v162, 10, v4
	v_add_u32_e32 v182, 0x8000, v180
	v_lshlrev_b32_e32 v192, 2, v180
	v_lshlrev_b32_e32 v193, 2, v181
	v_lshlrev_b32_e32 v194, 2, v182
	v_lshlrev_b32_e32 v195, 2, v183
	v_lshl_add_u32 v180, v164, 10, v2
	v_lshl_add_u32 v181, v163, 10, v2
	v_lshl_add_u32 v183, v162, 10, v2
	v_add_u32_e32 v182, 0x8000, v180
	v_lshlrev_b32_e32 v176, 1, v180
	v_lshlrev_b32_e32 v177, 1, v181
	v_lshlrev_b32_e32 v178, 1, v182
	v_lshlrev_b32_e32 v179, 1, v183
	global_load_dwordx4 v[252:255], v[138:139], off offset:512
	s_mov_b64 s[98:99], s[52:53]
	global_load_dwordx4 v[196:199], v192, s[98:99] offset:512
	global_load_dwordx4 v[202:205], v193, s[98:99] offset:512
	global_load_dwordx4 v[206:209], v194, s[98:99] offset:512
	global_load_dwordx4 v[210:213], v195, s[98:99] offset:512
	s_add_u32 s98, s98, 0x40000
	s_addc_u32 s99, s99, 0
	global_load_dwordx4 v[214:217], v192, s[98:99] offset:512
	global_load_dwordx4 v[218:221], v193, s[98:99] offset:512
	global_load_dwordx4 v[222:225], v194, s[98:99] offset:512
	global_load_dwordx4 v[226:229], v195, s[98:99] offset:512
	s_add_u32 s98, s98, 0x40000
	s_addc_u32 s99, s99, 0
	global_load_dwordx4 v[230:233], v192, s[98:99] offset:512
	global_load_dwordx4 v[234:237], v193, s[98:99] offset:512
	global_load_dwordx4 v[240:243], v194, s[98:99] offset:512
	global_load_dwordx4 v[244:247], v195, s[98:99] offset:512
	s_add_u32 s98, s98, 0x40000
	s_addc_u32 s99, s99, 0
	global_load_dwordx4 v[248:251], v192, s[98:99] offset:512
	global_load_dwordx4 v[168:171], v193, s[98:99] offset:512
	global_load_dwordx4 v[172:175], v194, s[98:99] offset:512
	global_load_dwordx4 v[188:191], v195, s[98:99] offset:512
	s_waitcnt lgkmcnt(0)
	s_barrier
	s_mov_b64 s[98:99], s[14:15]
	ds_read_b128 v[180:183], v6
	ds_read_b128 v[184:187], v7
	s_waitcnt vmcnt(15) lgkmcnt(1)
	v_pk_fma_f32 v[196:197], v[196:197], s[24:25], v[180:181] op_sel_hi:[1,0,1]
	v_pk_fma_f32 v[198:199], v[198:199], s[24:25], v[182:183] op_sel_hi:[1,0,1]
	ds_read_b128 v[180:183], v6 offset:16896
	v_pk_add_f32 v[196:197], v[196:197], v[252:253]
	v_pk_add_f32 v[198:199], v[198:199], v[254:255]
	v_cvt_pk_bf16_f32 v196, v196, v197
	v_cvt_pk_bf16_f32 v197, v198, v199
	global_store_dwordx2 v176, v[196:197], s[98:99]
	s_waitcnt vmcnt(15) lgkmcnt(1)
	v_pk_fma_f32 v[202:203], v[202:203], s[24:25], v[184:185] op_sel_hi:[1,0,1]
	v_pk_fma_f32 v[204:205], v[204:205], s[24:25], v[186:187] op_sel_hi:[1,0,1]
	ds_read_b128 v[184:187], v8
	v_pk_add_f32 v[202:203], v[202:203], v[252:253]
	v_pk_add_f32 v[204:205], v[204:205], v[254:255]
	v_cvt_pk_bf16_f32 v202, v202, v203
	v_cvt_pk_bf16_f32 v203, v204, v205
	global_store_dwordx2 v177, v[202:203], s[98:99]
	s_waitcnt vmcnt(15) lgkmcnt(1)
	v_pk_fma_f32 v[206:207], v[206:207], s[24:25], v[180:181] op_sel_hi:[1,0,1]
	v_pk_fma_f32 v[208:209], v[208:209], s[24:25], v[182:183] op_sel_hi:[1,0,1]
	v_pk_add_f32 v[206:207], v[206:207], v[252:253]
	v_pk_add_f32 v[208:209], v[208:209], v[254:255]
	v_cvt_pk_bf16_f32 v206, v206, v207
	v_cvt_pk_bf16_f32 v207, v208, v209
	global_store_dwordx2 v178, v[206:207], s[98:99]
	s_waitcnt vmcnt(15) lgkmcnt(0)
	v_pk_fma_f32 v[210:211], v[210:211], s[24:25], v[184:185] op_sel_hi:[1,0,1]
	v_pk_fma_f32 v[212:213], v[212:213], s[24:25], v[186:187] op_sel_hi:[1,0,1]
	v_pk_add_f32 v[210:211], v[210:211], v[252:253]
	v_pk_add_f32 v[212:213], v[212:213], v[254:255]
	v_cvt_pk_bf16_f32 v210, v210, v211
	v_cvt_pk_bf16_f32 v211, v212, v213
	global_store_dwordx2 v179, v[210:211], s[98:99]
	v_add_u32_e32 v6, 0x8400, v6
	v_add_u32_e32 v7, 0x8400, v7
	v_add_u32_e32 v8, 0x8400, v8
	s_add_u32 s98, s98, 0x20000
	s_addc_u32 s99, s99, 0
	ds_read_b128 v[180:183], v6
	ds_read_b128 v[184:187], v7
	s_waitcnt vmcnt(15) lgkmcnt(1)
	v_pk_fma_f32 v[214:215], v[214:215], s[24:25], v[180:181] op_sel_hi:[1,0,1]
	v_pk_fma_f32 v[216:217], v[216:217], s[24:25], v[182:183] op_sel_hi:[1,0,1]
	ds_read_b128 v[180:183], v6 offset:16896
	v_pk_add_f32 v[214:215], v[214:215], v[252:253]
	v_pk_add_f32 v[216:217], v[216:217], v[254:255]
	v_cvt_pk_bf16_f32 v214, v214, v215
	v_cvt_pk_bf16_f32 v215, v216, v217
	global_store_dwordx2 v176, v[214:215], s[98:99]
	s_waitcnt vmcnt(15) lgkmcnt(1)
	v_pk_fma_f32 v[218:219], v[218:219], s[24:25], v[184:185] op_sel_hi:[1,0,1]
	v_pk_fma_f32 v[220:221], v[220:221], s[24:25], v[186:187] op_sel_hi:[1,0,1]
	ds_read_b128 v[184:187], v8
	v_pk_add_f32 v[218:219], v[218:219], v[252:253]
	v_pk_add_f32 v[220:221], v[220:221], v[254:255]
	v_cvt_pk_bf16_f32 v218, v218, v219
	v_cvt_pk_bf16_f32 v219, v220, v221
	global_store_dwordx2 v177, v[218:219], s[98:99]
	s_waitcnt vmcnt(15) lgkmcnt(1)
; DI unsigned pack2(float a, float b) { const f32x2 v = {a, b}; const bf16x2_t r = __builtin_convertvector(v, bf16x2_t); return __builtin_bit_cast(unsigned, r); }
; DI void outproj_epilogue(const Params& p, const char* smem, const int m0, const int n0) {
;     ...
; #pragma unroll 4
;   for (int i = 0; i < 16; ++i) {
;     const int c = threadIdx.x + NT * i, row = c >> 5, ch = c & 31;
;     const float4 y = *(const float4*)(ct + row * CT_PITCH + 4 * ch);
;     const size_t o = (size_t)(m0 + row) * 1024 + n0 + 4 * ch;
;     const float4 xv = *(const float4*)(p.x + o), bv = *(const float4*)(p.b_out + n0 + 4 * ch);
;     uint2 r; r.x = pack2(ALPHA * xv.x + y.x + bv.x, ALPHA * xv.y + y.y + bv.y); r.y = pack2(ALPHA * xv.z + y.z + bv.z, ALPHA * xv.w + y.w + bv.w);
;     *(uint2*)(rbuf + o) = r;
;   }
; DI void phase_outproj(const Params& p, char* smem) {
;     ...
;   for (int tile = blockIdx.x, kit = 0; tile < (T / 256) * NTN; tile += gridDim.x, ++kit) {
;     int mt_, nt_; tile_coords<4>(tile, kit, T / 256, NTN, mt_, nt_);
;     const int m0 = mt_ * 256, n0b = nt_ * 256;
;     f32x4 acc[8][4];
;     gemm_tile_big(mix, wt, DM, m0, n0b, smem, acc);
;     stage_acc_big<0>(acc, smem, g, r16);
;     __syncthreads();
;     outproj_epilogue(p, smem, m0, n0b);
;     __syncthreads();
;     stage_acc_big<1>(acc, smem, g, r16);
;     __syncthreads();
;     outproj_epilogue(p, smem, m0, n0b + 128);
;     __syncthreads();
;   }
	v_pk_fma_f32 v[222:223], v[222:223], s[24:25], v[180:181] op_sel_hi:[1,0,1]
	v_pk_fma_f32 v[224:225], v[224:225], s[24:25], v[182:183] op_sel_hi:[1,0,1]
	v_pk_add_f32 v[222:223], v[222:223], v[252:253]
	v_pk_add_f32 v[224:225], v[224:225], v[254:255]
	v_cvt_pk_bf16_f32 v222, v222, v223
	v_cvt_pk_bf16_f32 v223, v224, v225
	global_store_dwordx2 v178, v[222:223], s[98:99]
	s_waitcnt vmcnt(15) lgkmcnt(0)
	v_pk_fma_f32 v[226:227], v[226:227], s[24:25], v[184:185] op_sel_hi:[1,0,1]
	v_pk_fma_f32 v[228:229], v[228:229], s[24:25], v[186:187] op_sel_hi:[1,0,1]
	v_pk_add_f32 v[226:227], v[226:227], v[252:253]
	v_pk_add_f32 v[228:229], v[228:229], v[254:255]
	v_cvt_pk_bf16_f32 v226, v226, v227
	v_cvt_pk_bf16_f32 v227, v228, v229
	global_store_dwordx2 v179, v[226:227], s[98:99]
	v_add_u32_e32 v6, 0x8400, v6
	v_add_u32_e32 v7, 0x8400, v7
	v_add_u32_e32 v8, 0x8400, v8
	s_add_u32 s98, s98, 0x20000
	s_addc_u32 s99, s99, 0
	ds_read_b128 v[180:183], v6
	ds_read_b128 v[184:187], v7
	s_waitcnt vmcnt(15) lgkmcnt(1)
	v_pk_fma_f32 v[230:231], v[230:231], s[24:25], v[180:181] op_sel_hi:[1,0,1]
	v_pk_fma_f32 v[232:233], v[232:233], s[24:25], v[182:183] op_sel_hi:[1,0,1]
	ds_read_b128 v[180:183], v6 offset:16896
	v_pk_add_f32 v[230:231], v[230:231], v[252:253]
	v_pk_add_f32 v[232:233], v[232:233], v[254:255]
	v_cvt_pk_bf16_f32 v230, v230, v231
	v_cvt_pk_bf16_f32 v231, v232, v233
	global_store_dwordx2 v176, v[230:231], s[98:99]
	s_waitcnt vmcnt(15) lgkmcnt(1)
	v_pk_fma_f32 v[234:235], v[234:235], s[24:25], v[184:185] op_sel_hi:[1,0,1]
	v_pk_fma_f32 v[236:237], v[236:237], s[24:25], v[186:187] op_sel_hi:[1,0,1]
	ds_read_b128 v[184:187], v8
	v_pk_add_f32 v[234:235], v[234:235], v[252:253]
	v_pk_add_f32 v[236:237], v[236:237], v[254:255]
	v_cvt_pk_bf16_f32 v234, v234, v235
	v_cvt_pk_bf16_f32 v235, v236, v237
	global_store_dwordx2 v177, v[234:235], s[98:99]
	s_waitcnt vmcnt(15) lgkmcnt(1)
	v_pk_fma_f32 v[240:241], v[240:241], s[24:25], v[180:181] op_sel_hi:[1,0,1]
	v_pk_fma_f32 v[242:243], v[242:243], s[24:25], v[182:183] op_sel_hi:[1,0,1]
	v_pk_add_f32 v[240:241], v[240:241], v[252:253]
	v_pk_add_f32 v[242:243], v[242:243], v[254:255]
	v_cvt_pk_bf16_f32 v240, v240, v241
	v_cvt_pk_bf16_f32 v241, v242, v243
	global_store_dwordx2 v178, v[240:241], s[98:99]
	s_waitcnt vmcnt(15) lgkmcnt(0)
	v_pk_fma_f32 v[244:245], v[244:245], s[24:25], v[184:185] op_sel_hi:[1,0,1]
	v_pk_fma_f32 v[246:247], v[246:247], s[24:25], v[186:187] op_sel_hi:[1,0,1]
	v_pk_add_f32 v[244:245], v[244:245], v[252:253]
	v_pk_add_f32 v[246:247], v[246:247], v[254:255]
	v_cvt_pk_bf16_f32 v244, v244, v245
	v_cvt_pk_bf16_f32 v245, v246, v247
	global_store_dwordx2 v179, v[244:245], s[98:99]
	v_add_u32_e32 v6, 0x8400, v6
	v_add_u32_e32 v7, 0x8400, v7
	v_add_u32_e32 v8, 0x8400, v8
	s_add_u32 s98, s98, 0x20000
	s_addc_u32 s99, s99, 0
	ds_read_b128 v[180:183], v6
	ds_read_b128 v[184:187], v7
	s_waitcnt vmcnt(15) lgkmcnt(1)
	v_pk_fma_f32 v[248:249], v[248:249], s[24:25], v[180:181] op_sel_hi:[1,0,1]
	v_pk_fma_f32 v[250:251], v[250:251], s[24:25], v[182:183] op_sel_hi:[1,0,1]
	ds_read_b128 v[180:183], v6 offset:16896
	v_pk_add_f32 v[248:249], v[248:249], v[252:253]
	v_pk_add_f32 v[250:251], v[250:251], v[254:255]
	v_cvt_pk_bf16_f32 v248, v248, v249
	v_cvt_pk_bf16_f32 v249, v250, v251
	global_store_dwordx2 v176, v[248:249], s[98:99]
	s_waitcnt vmcnt(15) lgkmcnt(1)
	v_pk_fma_f32 v[168:169], v[168:169], s[24:25], v[184:185] op_sel_hi:[1,0,1]
	v_pk_fma_f32 v[170:171], v[170:171], s[24:25], v[186:187] op_sel_hi:[1,0,1]
	ds_read_b128 v[184:187], v8
	v_pk_add_f32 v[168:169], v[168:169], v[252:253]
	v_pk_add_f32 v[170:171], v[170:171], v[254:255]
	v_cvt_pk_bf16_f32 v168, v168, v169
	v_cvt_pk_bf16_f32 v169, v170, v171
	global_store_dwordx2 v177, v[168:169], s[98:99]
	s_waitcnt vmcnt(15) lgkmcnt(1)
	v_pk_fma_f32 v[172:173], v[172:173], s[24:25], v[180:181] op_sel_hi:[1,0,1]
	v_pk_fma_f32 v[174:175], v[174:175], s[24:25], v[182:183] op_sel_hi:[1,0,1]
	v_pk_add_f32 v[172:173], v[172:173], v[252:253]
	v_pk_add_f32 v[174:175], v[174:175], v[254:255]
	v_cvt_pk_bf16_f32 v172, v172, v173
	v_cvt_pk_bf16_f32 v173, v174, v175
	global_store_dwordx2 v178, v[172:173], s[98:99]
	s_waitcnt vmcnt(15) lgkmcnt(0)
	v_pk_fma_f32 v[188:189], v[188:189], s[24:25], v[184:185] op_sel_hi:[1,0,1]
	v_pk_fma_f32 v[190:191], v[190:191], s[24:25], v[186:187] op_sel_hi:[1,0,1]
	v_pk_add_f32 v[188:189], v[188:189], v[252:253]
	v_pk_add_f32 v[190:191], v[190:191], v[254:255]
	v_cvt_pk_bf16_f32 v188, v188, v189
	v_cvt_pk_bf16_f32 v189, v190, v191
	global_store_dwordx2 v179, v[188:189], s[98:99]
	s_add_i32 s31, s31, s3
	s_add_i32 s34, s34, 1
	s_cmpk_lt_i32 s31, 0x200
	s_barrier
	s_cbranch_scc1 .LBB0_286
	s_branch .LBB0_303

; __global__ void __launch_bounds__(NT) hymba_fwd(Params p) {
	.amdhsa_kernel _Z9hymba_fwd6Params
		.amdhsa_group_segment_fixed_size 0
		.amdhsa_private_segment_fixed_size 0
		.amdhsa_kernarg_size 416
		.amdhsa_user_sgpr_count 2
		.amdhsa_user_sgpr_dispatch_ptr 0
		.amdhsa_user_sgpr_queue_ptr 0
		.amdhsa_user_sgpr_kernarg_segment_ptr 1
		.amdhsa_user_sgpr_dispatch_id 0
		.amdhsa_user_sgpr_kernarg_preload_length 0
		.amdhsa_user_sgpr_kernarg_preload_offset 0
		.amdhsa_user_sgpr_private_segment_size 0
		.amdhsa_uses_dynamic_stack 0
		.amdhsa_enable_private_segment 0
		.amdhsa_system_sgpr_workgroup_id_x 1
		.amdhsa_system_sgpr_workgroup_id_y 0
		.amdhsa_system_sgpr_workgroup_id_z 0
		.amdhsa_system_sgpr_workgroup_info 0
		.amdhsa_system_vgpr_workitem_id 0
		.amdhsa_next_free_vgpr 256
		.amdhsa_next_free_sgpr 102
		.amdhsa_accum_offset 256
		.amdhsa_reserve_vcc 1
		.amdhsa_float_round_mode_32 0
		.amdhsa_float_round_mode_16_64 0
		.amdhsa_float_denorm_mode_32 3
		.amdhsa_float_denorm_mode_16_64 3
		.amdhsa_dx10_clamp 1
		.amdhsa_ieee_mode 1
		.amdhsa_fp16_overflow 0
		.amdhsa_tg_split 0
		.amdhsa_exception_fp_ieee_invalid_op 0
		.amdhsa_exception_fp_denorm_src 0
		.amdhsa_exception_fp_ieee_div_zero 0
		.amdhsa_exception_fp_ieee_overflow 0
		.amdhsa_exception_fp_ieee_underflow 0
		.amdhsa_exception_fp_ieee_inexact 0
		.amdhsa_exception_int_div_zero 0
	.end_amdhsa_kernel

; __global__ void __launch_bounds__(NT) hymba_fwd(Params p) {
amdhsa.kernels:
  - .agpr_count:     0
    .args:
      - .offset:         0
        .size:           160
        .value_kind:     by_value
      - .offset:         160
        .size:           4
        .value_kind:     hidden_block_count_x
      - .offset:         164
        .size:           4
        .value_kind:     hidden_block_count_y
      - .offset:         168
        .size:           4
        .value_kind:     hidden_block_count_z
      - .offset:         172
        .size:           2
        .value_kind:     hidden_group_size_x
      - .offset:         174
        .size:           2
        .value_kind:     hidden_group_size_y
      - .offset:         176
        .size:           2
        .value_kind:     hidden_group_size_z
      - .offset:         178
        .size:           2
        .value_kind:     hidden_remainder_x
      - .offset:         180
        .size:           2
        .value_kind:     hidden_remainder_y
      - .offset:         182
        .size:           2
        .value_kind:     hidden_remainder_z
      - .offset:         200
        .size:           8
        .value_kind:     hidden_global_offset_x
      - .offset:         208
        .size:           8
        .value_kind:     hidden_global_offset_y
      - .offset:         216
        .size:           8
        .value_kind:     hidden_global_offset_z
      - .offset:         224
        .size:           2
        .value_kind:     hidden_grid_dims
      - .offset:         280
        .size:           4
        .value_kind:     hidden_dynamic_lds_size
    .group_segment_fixed_size: 0
    .kernarg_segment_align: 8
    .kernarg_segment_size: 416
    .language:       OpenCL C
    .language_version:
      - 2
      - 0
    .max_flat_workgroup_size: 512
    .name:           _Z9hymba_fwd6Params
    .private_segment_fixed_size: 0
    .sgpr_count:     108
    .sgpr_spill_count: 26
    .symbol:         _Z9hymba_fwd6Params.kd
    .uniform_work_group_size: 1
    .uses_dynamic_stack: false
    .vgpr_count:     256
    .vgpr_spill_count: 0
    .wavefront_size: 64
